# phase G fused final-norm store pass: norm weight quads loaded once, 32 output stores issued without draining the previous store each time
# baseline (speedup 1.0000x reference)
; __device__ __forceinline__ void phaseG(const Params& p, const int wv, const int rep, unsigned* bar, const bool fused) {
;     ...
;       ACC_FOREACH({
;         const float rs = rstd_l[rrow];
;         const f32x4 wv4 = *(const f32x4*)(wfin + bcol + rcol);
;         *(f32x4*)(p.out + O_Y + (size_t)(brow + rrow) * 1024 + bcol + rcol) = v * rs * wv4;
;       });
.LBB0_1134:
	s_or_b64 exec, exec, s[42:43]
	s_waitcnt lgkmcnt(0)
	s_barrier
	v_mbcnt_lo_u32_b32 v128, -1, 0
	v_mbcnt_hi_u32_b32 v128, -1, v128
	s_lshl_b32 s18, s86, 2
	v_ashrrev_i32_e32 v8, 2, v128
	v_and_b32_e32 v8, -4, v8
	v_add_u32_e32 v8, s74, v8
	s_add_u32 s4, s46, s18
	v_ashrrev_i32_e32 v9, 31, v8
	s_addc_u32 s5, s47, 0
	v_lshlrev_b64 v[10:11], 2, v[8:9]
	v_lshl_add_u64 v[8:9], s[4:5], 0, v[10:11]
	global_load_dwordx4 v[150:153], v[8:9], off
	global_load_dwordx4 v[154:157], v[8:9], off offset:64
	global_load_dwordx4 v[158:161], v[8:9], off offset:512
	global_load_dwordx4 v[162:165], v[8:9], off offset:576
	v_and_or_b32 v128, v128, 15, s65
	v_lshl_add_u32 v138, v128, 2, 16
	v_add_u32_e32 v144, 0x1000, v138
	ds_read2_b32 v[138:139], v144 offset1:16
	v_add_u32_e32 v128, s87, v128
	v_lshlrev_b64 v[142:143], 12, v[128:129]
	v_lshl_add_u64 v[142:143], s[48:49], 0, v[142:143]
	v_lshl_add_u64 v[142:143], v[142:143], 0, s[18:19]
	s_waitcnt lgkmcnt(0)
	v_pk_mul_f32 v[134:135], v[134:135], v[138:139] op_sel_hi:[1,0]
	v_pk_mul_f32 v[136:137], v[136:137], v[138:139] op_sel_hi:[1,0]
	v_lshl_add_u64 v[142:143], v[142:143], 0, v[10:11]
	v_pk_mul_f32 v[130:131], v[130:131], v[138:139] op_sel_hi:[1,0]
	v_pk_mul_f32 v[132:133], v[132:133], v[138:139] op_sel_hi:[1,0]
	v_pk_mul_f32 v[116:117], v[116:117], v[138:139] op_sel_hi:[1,0]
	v_pk_mul_f32 v[118:119], v[118:119], v[138:139] op_sel_hi:[1,0]
	v_pk_mul_f32 v[112:113], v[112:113], v[138:139] op_sel_hi:[1,0]
	v_pk_mul_f32 v[114:115], v[114:115], v[138:139] op_sel_hi:[1,0]
	s_waitcnt vmcnt(0)
	v_pk_mul_f32 v[12:13], v[150:151], v[136:137]
	v_pk_mul_f32 v[14:15], v[152:153], v[134:135]
	global_store_dwordx4 v[142:143], v[12:15], off sc1
	s_nop 1
	v_pk_mul_f32 v[12:13], v[154:155], v[132:133]
	v_pk_mul_f32 v[14:15], v[156:157], v[130:131]
	global_store_dwordx4 v[142:143], v[12:15], off offset:64 sc1
	s_nop 1
	v_pk_mul_f32 v[12:13], v[158:159], v[118:119]
	v_pk_mul_f32 v[14:15], v[160:161], v[116:117]
	global_store_dwordx4 v[142:143], v[12:15], off offset:512 sc1
	s_nop 1
	v_pk_mul_f32 v[12:13], v[162:163], v[114:115]
	v_pk_mul_f32 v[14:15], v[164:165], v[112:113]
	global_store_dwordx4 v[142:143], v[12:15], off offset:576 sc1
	s_nop 1
	v_mov_b32_e32 v113, v129
	v_add_u32_e32 v112, 16, v128
	v_lshlrev_b64 v[112:113], 12, v[112:113]
	v_lshl_add_u64 v[112:113], s[48:49], 0, v[112:113]
	v_mov_b32_e32 v114, v139
	v_lshl_add_u64 v[112:113], v[112:113], 0, s[18:19]
	v_pk_mul_f32 v[116:117], v[124:125], v[114:115] op_sel_hi:[1,0]
	v_pk_mul_f32 v[118:119], v[126:127], v[114:115] op_sel_hi:[1,0]
	v_lshl_add_u64 v[112:113], v[112:113], 0, v[10:11]
	v_pk_mul_f32 v[100:101], v[100:101], v[114:115] op_sel_hi:[1,0]
	v_pk_mul_f32 v[102:103], v[102:103], v[114:115] op_sel_hi:[1,0]
	v_pk_mul_f32 v[96:97], v[96:97], v[114:115] op_sel_hi:[1,0]
	v_pk_mul_f32 v[98:99], v[98:99], v[114:115] op_sel_hi:[1,0]
	v_pk_mul_f32 v[12:13], v[150:151], v[118:119]
	v_pk_mul_f32 v[14:15], v[152:153], v[116:117]
	global_store_dwordx4 v[112:113], v[12:15], off sc1
	s_nop 1
	v_pk_mul_f32 v[116:117], v[120:121], v[114:115] op_sel_hi:[1,0]
	v_pk_mul_f32 v[118:119], v[122:123], v[114:115] op_sel_hi:[1,0]
	v_pk_mul_f32 v[14:15], v[156:157], v[116:117]
	v_pk_mul_f32 v[12:13], v[154:155], v[118:119]
	global_store_dwordx4 v[112:113], v[12:15], off offset:64 sc1
	s_nop 1
	v_pk_mul_f32 v[12:13], v[158:159], v[102:103]
	v_pk_mul_f32 v[14:15], v[160:161], v[100:101]
	global_store_dwordx4 v[112:113], v[12:15], off offset:512 sc1
	s_nop 1
	v_pk_mul_f32 v[12:13], v[162:163], v[98:99]
	v_pk_mul_f32 v[14:15], v[164:165], v[96:97]
	global_store_dwordx4 v[112:113], v[12:15], off offset:576 sc1
	s_nop 1
	ds_read2_b32 v[98:99], v144 offset0:32 offset1:48
	v_mov_b32_e32 v97, v129
	v_add_u32_e32 v96, 32, v128
	v_lshlrev_b64 v[96:97], 12, v[96:97]
	v_lshl_add_u64 v[96:97], s[48:49], 0, v[96:97]
	v_lshl_add_u64 v[96:97], v[96:97], 0, s[18:19]
	s_waitcnt lgkmcnt(0)
	v_pk_mul_f32 v[100:101], v[110:111], v[98:99] op_sel_hi:[1,0]
	v_pk_mul_f32 v[102:103], v[108:109], v[98:99] op_sel_hi:[1,0]
	v_lshl_add_u64 v[96:97], v[96:97], 0, v[10:11]
	v_pk_mul_f32 v[84:85], v[84:85], v[98:99] op_sel_hi:[1,0]
	v_pk_mul_f32 v[86:87], v[86:87], v[98:99] op_sel_hi:[1,0]
	v_pk_mul_f32 v[80:81], v[80:81], v[98:99] op_sel_hi:[1,0]
	v_pk_mul_f32 v[82:83], v[82:83], v[98:99] op_sel_hi:[1,0]
	v_pk_mul_f32 v[14:15], v[152:153], v[102:103]
	v_pk_mul_f32 v[12:13], v[150:151], v[100:101]
	global_store_dwordx4 v[96:97], v[12:15], off sc1
	s_nop 1
	v_pk_mul_f32 v[100:101], v[104:105], v[98:99] op_sel_hi:[1,0]
	v_pk_mul_f32 v[102:103], v[106:107], v[98:99] op_sel_hi:[1,0]
	v_pk_mul_f32 v[14:15], v[156:157], v[100:101]
	v_pk_mul_f32 v[12:13], v[154:155], v[102:103]
	global_store_dwordx4 v[96:97], v[12:15], off offset:64 sc1
	s_nop 1
	v_pk_mul_f32 v[12:13], v[158:159], v[86:87]
	v_pk_mul_f32 v[14:15], v[160:161], v[84:85]
	global_store_dwordx4 v[96:97], v[12:15], off offset:512 sc1
	s_nop 1
	v_pk_mul_f32 v[12:13], v[162:163], v[82:83]
	v_pk_mul_f32 v[14:15], v[164:165], v[80:81]
	global_store_dwordx4 v[96:97], v[12:15], off offset:576 sc1
	s_nop 1
	v_mov_b32_e32 v81, v129
	v_add_u32_e32 v80, 48, v128
	v_lshlrev_b64 v[80:81], 12, v[80:81]
	v_lshl_add_u64 v[80:81], s[48:49], 0, v[80:81]
	v_mov_b32_e32 v82, v99
	v_lshl_add_u64 v[80:81], v[80:81], 0, s[18:19]
	v_pk_mul_f32 v[84:85], v[94:95], v[82:83] op_sel_hi:[1,0]
	v_pk_mul_f32 v[86:87], v[92:93], v[82:83] op_sel_hi:[1,0]
	v_lshl_add_u64 v[80:81], v[80:81], 0, v[10:11]
	v_pk_mul_f32 v[68:69], v[68:69], v[82:83] op_sel_hi:[1,0]
	v_pk_mul_f32 v[70:71], v[70:71], v[82:83] op_sel_hi:[1,0]
	v_pk_mul_f32 v[64:65], v[64:65], v[82:83] op_sel_hi:[1,0]
	v_pk_mul_f32 v[66:67], v[66:67], v[82:83] op_sel_hi:[1,0]
	v_pk_mul_f32 v[14:15], v[152:153], v[86:87]
	v_pk_mul_f32 v[12:13], v[150:151], v[84:85]
	global_store_dwordx4 v[80:81], v[12:15], off sc1
	s_nop 1
	v_pk_mul_f32 v[84:85], v[88:89], v[82:83] op_sel_hi:[1,0]
	v_pk_mul_f32 v[86:87], v[90:91], v[82:83] op_sel_hi:[1,0]
	v_pk_mul_f32 v[14:15], v[156:157], v[84:85]
	v_pk_mul_f32 v[12:13], v[154:155], v[86:87]
	global_store_dwordx4 v[80:81], v[12:15], off offset:64 sc1
	s_nop 1
	v_pk_mul_f32 v[12:13], v[158:159], v[70:71]
	v_pk_mul_f32 v[14:15], v[160:161], v[68:69]
	global_store_dwordx4 v[80:81], v[12:15], off offset:512 sc1
	s_nop 1
	v_pk_mul_f32 v[12:13], v[162:163], v[66:67]
	v_pk_mul_f32 v[14:15], v[164:165], v[64:65]
	global_store_dwordx4 v[80:81], v[12:15], off offset:576 sc1
	s_nop 1
	ds_read2_b32 v[66:67], v144 offset0:128 offset1:144
	v_mov_b32_e32 v65, v129
	v_add_u32_e32 v64, 0x80, v128
	v_lshlrev_b64 v[64:65], 12, v[64:65]
	v_lshl_add_u64 v[64:65], s[48:49], 0, v[64:65]
	v_lshl_add_u64 v[64:65], v[64:65], 0, s[18:19]
	s_waitcnt lgkmcnt(0)
; __device__ __forceinline__ void phaseG(const Params& p, const int wv, const int rep, unsigned* bar, const bool fused) {
;     ...
;       ACC_FOREACH({
;         const float rs = rstd_l[rrow];
;         const f32x4 wv4 = *(const f32x4*)(wfin + bcol + rcol);
;         *(f32x4*)(p.out + O_Y + (size_t)(brow + rrow) * 1024 + bcol + rcol) = v * rs * wv4;
;       });
	v_pk_mul_f32 v[68:69], v[78:79], v[66:67] op_sel_hi:[1,0]
	v_pk_mul_f32 v[70:71], v[76:77], v[66:67] op_sel_hi:[1,0]
	v_lshl_add_u64 v[64:65], v[64:65], 0, v[10:11]
	v_pk_mul_f32 v[52:53], v[52:53], v[66:67] op_sel_hi:[1,0]
	v_pk_mul_f32 v[54:55], v[54:55], v[66:67] op_sel_hi:[1,0]
	v_pk_mul_f32 v[48:49], v[48:49], v[66:67] op_sel_hi:[1,0]
	v_pk_mul_f32 v[50:51], v[50:51], v[66:67] op_sel_hi:[1,0]
	v_pk_mul_f32 v[14:15], v[152:153], v[70:71]
	v_pk_mul_f32 v[12:13], v[150:151], v[68:69]
	global_store_dwordx4 v[64:65], v[12:15], off sc1
	s_nop 1
	v_pk_mul_f32 v[68:69], v[72:73], v[66:67] op_sel_hi:[1,0]
	v_pk_mul_f32 v[70:71], v[74:75], v[66:67] op_sel_hi:[1,0]
	v_pk_mul_f32 v[14:15], v[156:157], v[68:69]
	v_pk_mul_f32 v[12:13], v[154:155], v[70:71]
	global_store_dwordx4 v[64:65], v[12:15], off offset:64 sc1
	s_nop 1
	v_pk_mul_f32 v[12:13], v[158:159], v[54:55]
	v_pk_mul_f32 v[14:15], v[160:161], v[52:53]
	global_store_dwordx4 v[64:65], v[12:15], off offset:512 sc1
	s_nop 1
	v_pk_mul_f32 v[12:13], v[162:163], v[50:51]
	v_pk_mul_f32 v[14:15], v[164:165], v[48:49]
	global_store_dwordx4 v[64:65], v[12:15], off offset:576 sc1
	s_nop 1
	v_mov_b32_e32 v49, v129
	v_add_u32_e32 v48, 0x90, v128
	v_lshlrev_b64 v[48:49], 12, v[48:49]
	v_lshl_add_u64 v[48:49], s[48:49], 0, v[48:49]
	v_mov_b32_e32 v50, v67
	v_lshl_add_u64 v[48:49], v[48:49], 0, s[18:19]
	v_pk_mul_f32 v[52:53], v[62:63], v[50:51] op_sel_hi:[1,0]
	v_pk_mul_f32 v[54:55], v[60:61], v[50:51] op_sel_hi:[1,0]
	v_lshl_add_u64 v[48:49], v[48:49], 0, v[10:11]
	v_pk_mul_f32 v[36:37], v[36:37], v[50:51] op_sel_hi:[1,0]
	v_pk_mul_f32 v[38:39], v[38:39], v[50:51] op_sel_hi:[1,0]
	v_pk_mul_f32 v[32:33], v[32:33], v[50:51] op_sel_hi:[1,0]
	v_pk_mul_f32 v[34:35], v[34:35], v[50:51] op_sel_hi:[1,0]
	v_pk_mul_f32 v[14:15], v[152:153], v[54:55]
	v_pk_mul_f32 v[12:13], v[150:151], v[52:53]
	global_store_dwordx4 v[48:49], v[12:15], off sc1
	s_nop 1
	v_pk_mul_f32 v[52:53], v[56:57], v[50:51] op_sel_hi:[1,0]
	v_pk_mul_f32 v[54:55], v[58:59], v[50:51] op_sel_hi:[1,0]
	v_pk_mul_f32 v[14:15], v[156:157], v[52:53]
	v_pk_mul_f32 v[12:13], v[154:155], v[54:55]
	global_store_dwordx4 v[48:49], v[12:15], off offset:64 sc1
	s_nop 1
	v_pk_mul_f32 v[12:13], v[158:159], v[38:39]
	v_pk_mul_f32 v[14:15], v[160:161], v[36:37]
	global_store_dwordx4 v[48:49], v[12:15], off offset:512 sc1
	s_nop 1
	v_pk_mul_f32 v[12:13], v[162:163], v[34:35]
	v_pk_mul_f32 v[14:15], v[164:165], v[32:33]
	global_store_dwordx4 v[48:49], v[12:15], off offset:576 sc1
	s_nop 1
	ds_read2_b32 v[34:35], v144 offset0:160 offset1:176
	v_mov_b32_e32 v33, v129
	v_add_u32_e32 v32, 0xa0, v128
	v_lshlrev_b64 v[32:33], 12, v[32:33]
	v_lshl_add_u64 v[32:33], s[48:49], 0, v[32:33]
	v_lshl_add_u64 v[32:33], v[32:33], 0, s[18:19]
	s_waitcnt lgkmcnt(0)
	v_pk_mul_f32 v[36:37], v[46:47], v[34:35] op_sel_hi:[1,0]
	v_pk_mul_f32 v[38:39], v[44:45], v[34:35] op_sel_hi:[1,0]
	v_lshl_add_u64 v[32:33], v[32:33], 0, v[10:11]
	v_pk_mul_f32 v[20:21], v[20:21], v[34:35] op_sel_hi:[1,0]
	v_pk_mul_f32 v[22:23], v[22:23], v[34:35] op_sel_hi:[1,0]
	v_pk_mul_f32 v[16:17], v[16:17], v[34:35] op_sel_hi:[1,0]
	v_pk_mul_f32 v[18:19], v[18:19], v[34:35] op_sel_hi:[1,0]
	v_add_u32_e32 v128, 0xb0, v128
	v_pk_mul_f32 v[14:15], v[152:153], v[38:39]
	v_pk_mul_f32 v[12:13], v[150:151], v[36:37]
	global_store_dwordx4 v[32:33], v[12:15], off sc1
	s_nop 1
	v_pk_mul_f32 v[36:37], v[40:41], v[34:35] op_sel_hi:[1,0]
	v_pk_mul_f32 v[38:39], v[42:43], v[34:35] op_sel_hi:[1,0]
	v_pk_mul_f32 v[14:15], v[156:157], v[36:37]
	v_pk_mul_f32 v[12:13], v[154:155], v[38:39]
	global_store_dwordx4 v[32:33], v[12:15], off offset:64 sc1
	s_nop 1
	v_pk_mul_f32 v[12:13], v[158:159], v[22:23]
	v_pk_mul_f32 v[14:15], v[160:161], v[20:21]
	global_store_dwordx4 v[32:33], v[12:15], off offset:512 sc1
	s_nop 1
	v_pk_mul_f32 v[12:13], v[162:163], v[18:19]
	v_pk_mul_f32 v[14:15], v[164:165], v[16:17]
	global_store_dwordx4 v[32:33], v[12:15], off offset:576 sc1
	s_nop 1
	v_lshlrev_b64 v[16:17], 12, v[128:129]
	v_lshl_add_u64 v[16:17], s[48:49], 0, v[16:17]
	v_lshl_add_u64 v[16:17], v[16:17], 0, s[18:19]
	v_mov_b32_e32 v18, v35
	v_lshl_add_u64 v[16:17], v[16:17], 0, v[10:11]
	v_pk_mul_f32 v[10:11], v[30:31], v[18:19] op_sel_hi:[1,0]
	v_pk_mul_f32 v[20:21], v[28:29], v[18:19] op_sel_hi:[1,0]
	v_pk_mul_f32 v[12:13], v[150:151], v[10:11]
	v_pk_mul_f32 v[14:15], v[152:153], v[20:21]
	global_store_dwordx4 v[16:17], v[12:15], off sc1
	s_nop 1
	v_pk_mul_f32 v[20:21], v[26:27], v[18:19] op_sel_hi:[1,0]
	v_pk_mul_f32 v[14:15], v[24:25], v[18:19] op_sel_hi:[1,0]
	v_pk_mul_f32 v[10:11], v[154:155], v[20:21]
	v_pk_mul_f32 v[12:13], v[156:157], v[14:15]
	global_store_dwordx4 v[16:17], v[10:13], off offset:64 sc1
	s_nop 1
	v_pk_mul_f32 v[14:15], v[4:5], v[18:19] op_sel_hi:[1,0]
	v_pk_mul_f32 v[4:5], v[6:7], v[18:19] op_sel_hi:[1,0]
	v_pk_mul_f32 v[6:7], v[160:161], v[14:15]
	v_pk_mul_f32 v[4:5], v[158:159], v[4:5]
	global_store_dwordx4 v[16:17], v[4:7], off offset:512 sc1
	s_nop 1
	v_pk_mul_f32 v[8:9], v[0:1], v[18:19] op_sel_hi:[1,0]
	v_pk_mul_f32 v[0:1], v[2:3], v[18:19] op_sel_hi:[1,0]
	v_pk_mul_f32 v[2:3], v[164:165], v[8:9]
	v_pk_mul_f32 v[0:1], v[162:163], v[0:1]
	global_store_dwordx4 v[16:17], v[0:3], off offset:576 sc1
	s_nop 1
